# scan producer: per-chunk loads via SGPR base + VGPR offset (no per-load address math), kka/kd stored with two ds_write_b128 per item
# baseline (speedup 1.0000x reference)
.LBB0_59:
	v_lshrrev_b32_e32 v59, 2, v61
	v_lshlrev_b32_e32 v59, 8, v59
	v_lshl_or_b32 v59, v15, 4, v59
	v_and_b32_e32 v60, 3, v61
	v_lshl_or_b32 v59, v60, 2, v59
	v_add_u32_e32 v59, 0x20100, v59
	s_ashr_i32 s4, s34, 5
	s_ashr_i32 s5, s4, 31
	s_lshl_b64 s[4:5], s[4:5], 25
	v_readlane_b32 s6, v243, 21
	v_readlane_b32 s7, v243, 22
	s_add_u32 s28, s6, s4
	s_addc_u32 s29, s7, s5
	v_readlane_b32 s4, v241, 16
	v_readlane_b32 s5, v241, 17
	s_waitcnt vmcnt(0)
	v_lshlrev_b32_e32 v4, 1, v15
	v_readlane_b32 s4, v243, 7
	v_lshl_or_b32 v4, s64, 5, v4
	v_mov_b32_e32 v5, v180
	v_readlane_b32 s5, v243, 8
	v_readlane_b32 s8, v241, 20
	v_readlane_b32 s9, v241, 21
	v_lshl_add_u64 v[16:17], s[4:5], 0, v[4:5]
	v_cndmask_b32_e64 v4, v63, v61, s[42:43]
	v_ashrrev_i32_e32 v5, 31, v4
	v_lshl_add_u64 v[4:5], v[4:5], 0, s[80:81]
	v_lshlrev_b64 v[6:7], 9, v[4:5]
	v_or_b32_e32 v6, s37, v6
	v_or_b32_e32 v4, v6, v14
	v_mov_b32_e32 v5, v7
	v_lshlrev_b64 v[4:5], 1, v[4:5]
	v_readlane_b32 s8, v243, 17
	s_add_u32 s34, s28, 0x4000000
	v_lshl_add_u64 v[8:9], s[44:45], 0, v[4:5]
	v_lshl_add_u64 v[10:11], s[46:47], 0, v[4:5]
	v_readlane_b32 s9, v243, 18
	s_addc_u32 s35, s29, 0
	global_load_dwordx2 v[8:9], v[8:9], off
	v_or_b32_e32 v0, s37, v14
	global_load_dwordx2 v[54:55], v[10:11], off
	v_lshl_add_u64 v[10:11], s[8:9], 0, v[4:5]
	global_load_dwordx2 v[86:87], v[10:11], off
	v_lshl_add_u64 v[10:11], s[34:35], 0, v[4:5]
	global_load_dwordx2 v[56:57], v[10:11], off
	v_lshlrev_b32_e32 v0, 2, v0
	v_readlane_b32 s10, v241, 22
	v_readlane_b32 s11, v241, 23
	v_lshl_add_u64 v[10:11], v[6:7], 1, v[16:17]
	v_cndmask_b32_e64 v6, v65, v64, s[42:43]
	v_ashrrev_i32_e32 v7, 31, v6
	v_lshl_add_u64 v[6:7], v[6:7], 0, s[80:81]
	v_lshlrev_b64 v[6:7], 9, v[6:7]
	global_load_dwordx4 v[0:3], v0, s[10:11]
	v_or_b32_e32 v6, s37, v6
	v_or_b32_e32 v12, v6, v14
	v_mov_b32_e32 v13, v7
	v_lshl_add_u64 v[50:51], v[6:7], 1, v[16:17]
	v_cndmask_b32_e64 v6, v67, v66, s[42:43]
	v_lshlrev_b64 v[12:13], 1, v[12:13]
	v_ashrrev_i32_e32 v7, 31, v6
	v_lshl_add_u64 v[18:19], s[44:45], 0, v[12:13]
	v_lshl_add_u64 v[6:7], v[6:7], 0, s[80:81]
	global_load_dwordx2 v[34:35], v[18:19], off
	v_lshl_add_u64 v[18:19], s[46:47], 0, v[12:13]
	v_lshlrev_b64 v[6:7], 9, v[6:7]
	global_load_dwordx2 v[38:39], v[18:19], off
	v_lshl_add_u64 v[18:19], s[8:9], 0, v[12:13]
	v_or_b32_e32 v6, s37, v6
	global_load_dwordx2 v[40:41], v[18:19], off
	v_lshl_add_u64 v[18:19], s[34:35], 0, v[12:13]
	v_lshl_add_u64 v[52:53], s[28:29], 0, v[12:13]
	v_or_b32_e32 v12, v6, v14
	v_mov_b32_e32 v13, v7
	v_lshlrev_b64 v[12:13], 1, v[12:13]
	v_lshl_add_u64 v[44:45], v[6:7], 1, v[16:17]
	v_cndmask_b32_e64 v6, v69, v68, s[42:43]
	global_load_dwordx2 v[36:37], v[18:19], off
	v_lshl_add_u64 v[18:19], s[44:45], 0, v[12:13]
	v_ashrrev_i32_e32 v7, 31, v6
	global_load_dwordx2 v[26:27], v[18:19], off
	v_lshl_add_u64 v[18:19], s[46:47], 0, v[12:13]
	v_lshl_add_u64 v[6:7], v[6:7], 0, s[80:81]
	global_load_dwordx2 v[30:31], v[18:19], off
	v_lshl_add_u64 v[18:19], s[8:9], 0, v[12:13]
	v_lshlrev_b64 v[6:7], 9, v[6:7]
	v_lshl_add_u64 v[4:5], s[28:29], 0, v[4:5]
	global_load_dwordx2 v[32:33], v[18:19], off
	v_lshl_add_u64 v[18:19], s[34:35], 0, v[12:13]
	v_or_b32_e32 v6, s37, v6
	global_load_dwordx2 v[28:29], v[18:19], off
	v_or_b32_e32 v18, v6, v14
	v_mov_b32_e32 v19, v7
	v_lshl_add_u64 v[48:49], v[6:7], 1, v[16:17]
	global_load_dwordx2 v[6:7], v[4:5], off
	v_lshlrev_b64 v[42:43], 1, v[18:19]
	v_lshl_add_u64 v[18:19], s[44:45], 0, v[42:43]
	v_lshl_add_u64 v[20:21], s[46:47], 0, v[42:43]
	v_lshl_add_u64 v[22:23], s[8:9], 0, v[42:43]
	global_load_dwordx2 v[18:19], v[18:19], off
	v_lshl_add_u64 v[46:47], s[28:29], 0, v[42:43]
	global_load_dwordx2 v[20:21], v[20:21], off
	v_lshl_add_u64 v[12:13], s[28:29], 0, v[12:13]
	global_load_dwordx2 v[24:25], v[22:23], off
	v_lshl_add_u64 v[22:23], s[34:35], 0, v[42:43]
	global_load_dwordx2 v[22:23], v[22:23], off
	s_mov_b32 s10, 0x3d800000
	v_readlane_b32 s6, v241, 18
	s_mov_b32 s4, 0
	s_mov_b32 s5, 0x10000
	s_mov_b32 s6, 0
	v_readlane_b32 s7, v241, 19
	v_readlane_b32 s12, v241, 24
	v_readlane_b32 s13, v241, 25
	v_readlane_b32 s14, v241, 26
	v_readlane_b32 s15, v241, 27
	v_readlane_b32 s16, v241, 28
	v_readlane_b32 s17, v241, 29
	s_waitcnt vmcnt(0)
	v_lshlrev_b32_e32 v43, 16, v8
	v_and_b32_e32 v42, 0xffff0000, v8
	global_load_ushort v8, v[10:11], off
	v_readlane_b32 s18, v241, 30
	s_waitcnt vmcnt(16)
	v_lshlrev_b32_e32 v84, 16, v86
	v_and_b32_e32 v83, 0xffff0000, v86
	s_waitcnt vmcnt(15)
	v_cvt_f32_f16_e32 v88, v56
	v_cvt_f32_f16_sdwa v89, v56 dst_sel:DWORD dst_unused:UNUSED_PAD src0_sel:WORD_1
	v_lshlrev_b32_e32 v82, 16, v87
	v_and_b32_e32 v81, 0xffff0000, v87
	v_lshlrev_b32_e32 v86, 16, v54
	v_pk_add_f32 v[90:91], v[88:89], -1.0 op_sel_hi:[1,0]
	v_and_b32_e32 v87, 0xffff0000, v54
	v_cvt_pk_f16_f32 v10, v84, v83
	v_mul_f32_e32 v85, v88, v84
	s_waitcnt vmcnt(14)
	v_pk_fma_f32 v[90:91], v[0:1], v[90:91], 1.0 op_sel_hi:[1,1,0]
	v_mul_f32_e32 v83, v89, v83
	v_pk_mul_f32 v[86:87], v[90:91], v[86:87]
	v_cvt_f32_f16_e32 v90, v57
	v_cvt_f32_f16_sdwa v91, v57 dst_sel:DWORD dst_unused:UNUSED_PAD src0_sel:WORD_1
	v_lshlrev_b32_e32 v88, 16, v55
	v_and_b32_e32 v89, 0xffff0000, v55
	v_cvt_pk_f16_f32 v11, v82, v81
	v_pk_add_f32 v[94:95], v[90:91], -1.0 op_sel_hi:[1,0]
	v_mul_f32_e32 v93, v90, v82
	v_pk_fma_f32 v[94:95], v[2:3], v[94:95], 1.0 op_sel_hi:[1,1,0]
	v_mul_f32_e32 v81, v91, v81
	v_pk_mul_f32 v[88:89], v[94:95], v[88:89]
	global_load_dwordx2 v[52:53], v[52:53], off
	s_nop 0
	global_load_ushort v90, v[50:51], off
	s_nop 0
	global_load_dwordx2 v[50:51], v[12:13], off
	global_load_ushort v91, v[44:45], off
	s_nop 0
	global_load_dwordx2 v[44:45], v[46:47], off
	global_load_ushort v94, v[48:49], off
	v_cvt_pk_f16_f32 v54, v85, v83
	v_cvt_pk_f16_f32 v56, v86, v87
	v_cvt_pk_f16_f32 v55, v93, v81
	v_cvt_pk_f16_f32 v57, v88, v89
	v_and_b32_e32 v46, 0xffff0000, v9
	v_lshlrev_b32_e32 v47, 16, v9
	v_mov_b32_e32 v84, v87
	v_pk_mov_b32 v[48:49], v[46:47], v[42:43] op_sel:[1,0]
	v_mov_b32_e32 v82, v88
	v_mov_b32_e32 v92, v89
	v_readlane_b32 s19, v241, 31
	s_waitcnt vmcnt(11)
	v_cvt_f32_f16_e64 v4, -v6
	v_cvt_f32_f16_sdwa v5, -v6 dst_sel:DWORD dst_unused:UNUSED_PAD src0_sel:WORD_1
	v_cvt_f32_f16_e64 v6, -v7
	v_cvt_f32_f16_sdwa v7, -v7 dst_sel:DWORD dst_unused:UNUSED_PAD src0_sel:WORD_1
	v_exp_f32_e32 v4, v4
	v_exp_f32_e32 v5, v5
	v_exp_f32_e32 v6, v6
	v_exp_f32_e32 v7, v7
	ds_write_b128 v70, v[4:7]
	ds_write_b32 v70, v85 offset:512
	ds_write_b32 v70, v83 offset:516
	ds_write_b32 v70, v93 offset:520
	ds_write_b32 v70, v81 offset:524
	ds_write_b64 v70, v[86:87] offset:768
	ds_write_b64 v70, v[88:89] offset:776
	v_mul_f32_e32 v4, v4, v43
	v_mul_f32_e32 v5, v5, v42
	v_cvt_pk_f16_f32 v12, v43, v42
	v_fma_f32 v4, v86, v43, 0
	v_mov_b32_e32 v5, v180
	v_pk_fma_f32 v[4:5], v[84:85], v[42:43], v[4:5]
	v_mul_f32_e32 v6, v6, v47
	v_mul_f32_e32 v7, v7, v46
	v_pk_fma_f32 v[4:5], v[82:83], v[48:49], v[4:5]
	v_cvt_pk_f16_f32 v13, v47, v46
	v_pk_fma_f32 v[4:5], v[92:93], v[46:47], v[4:5]
	v_mov_b32_e32 v6, v180
	v_mul_f32_e32 v7, v81, v46
	ds_write_b128 v70, v[10:13] offset:256
	v_mov_b32_dpp v6, v4 row_ror:1 row_mask:0xf bank_mask:0xf
	v_pk_add_f32 v[4:5], v[4:5], v[6:7]
	v_mov_b32_e32 v7, v180
	v_mov_b32_e32 v6, v180
	s_waitcnt vmcnt(0)
	v_lshlrev_b32_e32 v8, 16, v8
	v_mov_b32_dpp v7, v5 row_ror:1 row_mask:0xf bank_mask:0xf
	v_mov_b32_dpp v6, v4 row_ror:2 row_mask:0xf bank_mask:0xf
	v_pk_add_f32 v[4:5], v[4:5], v[6:7]
	v_mov_b32_e32 v7, v180
	v_mov_b32_e32 v6, v180
	v_lshlrev_b32_e32 v43, 16, v34
	v_mov_b32_dpp v7, v5 row_ror:2 row_mask:0xf bank_mask:0xf
	v_mov_b32_dpp v6, v4 row_ror:4 row_mask:0xf bank_mask:0xf
	v_pk_add_f32 v[4:5], v[4:5], v[6:7]
	v_mov_b32_e32 v7, v180
	v_mov_b32_e32 v6, v180
	v_and_b32_e32 v42, 0xffff0000, v34
	v_mov_b32_dpp v7, v5 row_ror:4 row_mask:0xf bank_mask:0xf
	v_mov_b32_dpp v6, v4 row_ror:8 row_mask:0xf bank_mask:0xf
	v_pk_add_f32 v[4:5], v[4:5], v[6:7]
	v_mov_b32_e32 v7, v180
	v_pk_mul_f32 v[10:11], v[4:5], v[8:9]
	v_and_b32_e32 v34, 0xffff0000, v40
	v_mov_b32_dpp v7, v5 row_ror:8 row_mask:0xf bank_mask:0xf
	v_pk_add_f32 v[4:5], v[4:5], v[6:7]
	v_lshlrev_b32_e32 v46, 16, v41
	v_mov_b32_e32 v11, v5
	v_pk_mul_f32 v[4:5], v[10:11], s[10:11] op_sel_hi:[1,0]
	v_mov_b32_e32 v11, v180
	v_mov_b32_e32 v9, v4
	v_mov_b32_e32 v10, v5
	ds_write_b32 v59, v8 offset:0
	v_lshlrev_b32_e32 v9, 16, v40
	v_and_b32_e32 v54, 0xffff0000, v41
	s_waitcnt vmcnt(5)
	v_cvt_f32_f16_e64 v4, -v52
	v_cvt_f32_f16_sdwa v5, -v52 dst_sel:DWORD dst_unused:UNUSED_PAD src0_sel:WORD_1
	v_cvt_f32_f16_e64 v6, -v53
	v_cvt_f32_f16_sdwa v7, -v53 dst_sel:DWORD dst_unused:UNUSED_PAD src0_sel:WORD_1
	v_cvt_f32_f16_e32 v40, v36
	v_cvt_f32_f16_sdwa v41, v36 dst_sel:DWORD dst_unused:UNUSED_PAD src0_sel:WORD_1
	v_cvt_f32_f16_e32 v52, v37
	v_cvt_f32_f16_sdwa v53, v37 dst_sel:DWORD dst_unused:UNUSED_PAD src0_sel:WORD_1
	v_exp_f32_e32 v4, v4
	v_exp_f32_e32 v5, v5
	v_exp_f32_e32 v6, v6
	v_exp_f32_e32 v7, v7
	v_pk_add_f32 v[48:49], v[40:41], -1.0 op_sel_hi:[1,0]
	v_lshlrev_b32_e32 v12, 16, v38
	v_and_b32_e32 v13, 0xffff0000, v38
	v_pk_fma_f32 v[48:49], v[0:1], v[48:49], 1.0 op_sel_hi:[1,1,0]
	v_pk_add_f32 v[56:57], v[52:53], -1.0 op_sel_hi:[1,0]
	v_pk_mul_f32 v[48:49], v[48:49], v[12:13]
	v_lshlrev_b32_e32 v12, 16, v39
	v_and_b32_e32 v13, 0xffff0000, v39
	v_pk_fma_f32 v[56:57], v[2:3], v[56:57], 1.0 op_sel_hi:[1,1,0]
	v_cvt_pk_f16_f32 v10, v9, v34
	v_mul_f32_e32 v47, v40, v9
	v_mul_f32_e32 v41, v41, v34
	v_mul_f32_e32 v55, v52, v46
	v_pk_mul_f32 v[56:57], v[56:57], v[12:13]
	v_mul_f32_e32 v9, v53, v54
	v_cvt_pk_f16_f32 v36, v47, v41
	v_cvt_pk_f16_f32 v38, v48, v49
	v_cvt_pk_f16_f32 v37, v55, v9
	v_cvt_pk_f16_f32 v39, v56, v57
	ds_write_b128 v70, v[4:7] offset:16384
	ds_write_b32 v70, v47 offset:16896
	ds_write_b32 v70, v41 offset:16900
	ds_write_b32 v70, v55 offset:16904
	ds_write_b32 v70, v9 offset:16908
	ds_write_b64 v70, v[48:49] offset:17152
	ds_write_b64 v70, v[56:57] offset:17160
	v_mul_f32_e32 v4, v4, v43
	v_mul_f32_e32 v5, v5, v42
	v_cvt_pk_f16_f32 v11, v46, v54
	v_and_b32_e32 v34, 0xffff0000, v35
	v_lshlrev_b32_e32 v35, 16, v35
	v_cvt_pk_f16_f32 v12, v43, v42
	v_fma_f32 v4, v48, v43, 0
	v_mov_b32_e32 v46, v49
	v_mov_b32_e32 v5, v180
	v_pk_mov_b32 v[36:37], v[34:35], v[42:43] op_sel:[1,0]
	v_pk_fma_f32 v[4:5], v[46:47], v[42:43], v[4:5]
	v_mov_b32_e32 v40, v56
	v_mul_f32_e32 v6, v6, v35
	v_mul_f32_e32 v7, v7, v34
	v_pk_fma_f32 v[4:5], v[40:41], v[36:37], v[4:5]
	v_mov_b32_e32 v54, v57
	v_cvt_pk_f16_f32 v13, v35, v34
	v_pk_fma_f32 v[4:5], v[54:55], v[34:35], v[4:5]
	v_mov_b32_e32 v6, v180
	v_mul_f32_e32 v7, v9, v34
	s_waitcnt vmcnt(4)
	v_lshlrev_b32_e32 v8, 16, v90
	v_mov_b32_dpp v6, v4 row_ror:1 row_mask:0xf bank_mask:0xf
	v_pk_add_f32 v[4:5], v[4:5], v[6:7]
	v_mov_b32_e32 v7, v180
	v_mov_b32_e32 v6, v180
	ds_write_b128 v70, v[10:13] offset:16640
	v_mov_b32_dpp v7, v5 row_ror:1 row_mask:0xf bank_mask:0xf
	v_mov_b32_dpp v6, v4 row_ror:2 row_mask:0xf bank_mask:0xf
	v_pk_add_f32 v[4:5], v[4:5], v[6:7]
	v_mov_b32_e32 v7, v180
	v_mov_b32_e32 v6, v180
	v_lshlrev_b32_e32 v35, 16, v26
	v_mov_b32_dpp v7, v5 row_ror:2 row_mask:0xf bank_mask:0xf
	v_mov_b32_dpp v6, v4 row_ror:4 row_mask:0xf bank_mask:0xf
	v_pk_add_f32 v[4:5], v[4:5], v[6:7]
	v_mov_b32_e32 v7, v180
	v_mov_b32_e32 v6, v180
	v_and_b32_e32 v34, 0xffff0000, v26
	v_mov_b32_dpp v7, v5 row_ror:4 row_mask:0xf bank_mask:0xf
	v_mov_b32_dpp v6, v4 row_ror:8 row_mask:0xf bank_mask:0xf
	v_pk_add_f32 v[4:5], v[4:5], v[6:7]
	v_mov_b32_e32 v7, v180
	v_pk_mul_f32 v[10:11], v[4:5], v[8:9]
	v_and_b32_e32 v26, 0xffff0000, v32
	v_mov_b32_dpp v7, v5 row_ror:8 row_mask:0xf bank_mask:0xf
	v_pk_add_f32 v[4:5], v[4:5], v[6:7]
	v_lshlrev_b32_e32 v36, 16, v33
	v_mov_b32_e32 v11, v5
	v_pk_mul_f32 v[4:5], v[10:11], s[10:11] op_sel_hi:[1,0]
	v_mov_b32_e32 v11, v180
	v_mov_b32_e32 v9, v4
	v_mov_b32_e32 v10, v5
	ds_write_b32 v59, v8 offset:1024
	v_lshlrev_b32_e32 v9, 16, v32
	v_and_b32_e32 v42, 0xffff0000, v33
	s_waitcnt vmcnt(3)
	v_cvt_f32_f16_e64 v4, -v50
	v_cvt_f32_f16_sdwa v5, -v50 dst_sel:DWORD dst_unused:UNUSED_PAD src0_sel:WORD_1
	v_cvt_f32_f16_e64 v6, -v51
	v_cvt_f32_f16_sdwa v7, -v51 dst_sel:DWORD dst_unused:UNUSED_PAD src0_sel:WORD_1
	v_cvt_f32_f16_e32 v32, v28
	v_cvt_f32_f16_sdwa v33, v28 dst_sel:DWORD dst_unused:UNUSED_PAD src0_sel:WORD_1
	v_cvt_f32_f16_e32 v40, v29
	v_cvt_f32_f16_sdwa v41, v29 dst_sel:DWORD dst_unused:UNUSED_PAD src0_sel:WORD_1
	v_exp_f32_e32 v4, v4
	v_exp_f32_e32 v5, v5
	v_exp_f32_e32 v6, v6
	v_exp_f32_e32 v7, v7
	v_pk_add_f32 v[38:39], v[32:33], -1.0 op_sel_hi:[1,0]
	v_lshlrev_b32_e32 v12, 16, v30
	v_and_b32_e32 v13, 0xffff0000, v30
	v_pk_fma_f32 v[38:39], v[0:1], v[38:39], 1.0 op_sel_hi:[1,1,0]
	v_pk_add_f32 v[46:47], v[40:41], -1.0 op_sel_hi:[1,0]
	v_pk_mul_f32 v[38:39], v[38:39], v[12:13]
	v_lshlrev_b32_e32 v12, 16, v31
	v_and_b32_e32 v13, 0xffff0000, v31
	v_pk_fma_f32 v[46:47], v[2:3], v[46:47], 1.0 op_sel_hi:[1,1,0]
	v_cvt_pk_f16_f32 v10, v9, v26
	v_mul_f32_e32 v37, v32, v9
	v_mul_f32_e32 v33, v33, v26
	v_mul_f32_e32 v43, v40, v36
	v_pk_mul_f32 v[46:47], v[46:47], v[12:13]
	v_mul_f32_e32 v9, v41, v42
	v_cvt_pk_f16_f32 v28, v37, v33
	v_cvt_pk_f16_f32 v30, v38, v39
	v_cvt_pk_f16_f32 v29, v43, v9
	v_cvt_pk_f16_f32 v31, v46, v47
	ds_write_b128 v70, v[4:7] offset:32768
	ds_write_b32 v70, v37 offset:33280
	ds_write_b32 v70, v33 offset:33284
	ds_write_b32 v70, v43 offset:33288
	ds_write_b32 v70, v9 offset:33292
	ds_write_b64 v70, v[38:39] offset:33536
	ds_write_b64 v70, v[46:47] offset:33544
	v_mul_f32_e32 v4, v4, v35
	v_mul_f32_e32 v5, v5, v34
	v_cvt_pk_f16_f32 v11, v36, v42
	v_and_b32_e32 v26, 0xffff0000, v27
	v_lshlrev_b32_e32 v27, 16, v27
	v_cvt_pk_f16_f32 v12, v35, v34
	v_fma_f32 v4, v38, v35, 0
	v_mov_b32_e32 v36, v39
	v_mov_b32_e32 v5, v180
	v_pk_mov_b32 v[28:29], v[26:27], v[34:35] op_sel:[1,0]
	v_pk_fma_f32 v[4:5], v[36:37], v[34:35], v[4:5]
	v_mov_b32_e32 v32, v46
	v_mul_f32_e32 v6, v6, v27
	v_mul_f32_e32 v7, v7, v26
	v_pk_fma_f32 v[4:5], v[32:33], v[28:29], v[4:5]
	v_mov_b32_e32 v42, v47
	v_cvt_pk_f16_f32 v13, v27, v26
	v_pk_fma_f32 v[4:5], v[42:43], v[26:27], v[4:5]
	v_mov_b32_e32 v6, v180
	v_mul_f32_e32 v7, v9, v26
	s_waitcnt vmcnt(2)
	v_lshlrev_b32_e32 v8, 16, v91
	v_mov_b32_dpp v6, v4 row_ror:1 row_mask:0xf bank_mask:0xf
	v_pk_add_f32 v[4:5], v[4:5], v[6:7]
	v_mov_b32_e32 v7, v180
	v_mov_b32_e32 v6, v180
	ds_write_b128 v70, v[10:13] offset:33024
	v_mov_b32_dpp v7, v5 row_ror:1 row_mask:0xf bank_mask:0xf
	v_mov_b32_dpp v6, v4 row_ror:2 row_mask:0xf bank_mask:0xf
	v_pk_add_f32 v[4:5], v[4:5], v[6:7]
	v_mov_b32_e32 v7, v180
	v_mov_b32_e32 v6, v180
	v_lshlrev_b32_e32 v27, 16, v18
	v_mov_b32_dpp v7, v5 row_ror:2 row_mask:0xf bank_mask:0xf
	v_mov_b32_dpp v6, v4 row_ror:4 row_mask:0xf bank_mask:0xf
	v_pk_add_f32 v[4:5], v[4:5], v[6:7]
	v_mov_b32_e32 v7, v180
	v_mov_b32_e32 v6, v180
	v_and_b32_e32 v26, 0xffff0000, v18
	v_mov_b32_dpp v7, v5 row_ror:4 row_mask:0xf bank_mask:0xf
	v_mov_b32_dpp v6, v4 row_ror:8 row_mask:0xf bank_mask:0xf
	v_pk_add_f32 v[4:5], v[4:5], v[6:7]
	v_mov_b32_e32 v7, v180
	v_pk_mul_f32 v[10:11], v[4:5], v[8:9]
	v_and_b32_e32 v18, 0xffff0000, v24
	v_mov_b32_dpp v7, v5 row_ror:8 row_mask:0xf bank_mask:0xf
	v_pk_add_f32 v[4:5], v[4:5], v[6:7]
	v_lshlrev_b32_e32 v28, 16, v25
	v_mov_b32_e32 v11, v5
	v_pk_mul_f32 v[4:5], v[10:11], s[10:11] op_sel_hi:[1,0]
	v_mov_b32_e32 v11, v180
	v_mov_b32_e32 v9, v4
	v_mov_b32_e32 v10, v5
	ds_write_b32 v59, v8 offset:2048
	v_lshlrev_b32_e32 v9, 16, v24
	v_and_b32_e32 v34, 0xffff0000, v25
	s_waitcnt vmcnt(1)
	v_cvt_f32_f16_e64 v4, -v44
	v_cvt_f32_f16_sdwa v5, -v44 dst_sel:DWORD dst_unused:UNUSED_PAD src0_sel:WORD_1
	v_cvt_f32_f16_e64 v6, -v45
	v_cvt_f32_f16_sdwa v7, -v45 dst_sel:DWORD dst_unused:UNUSED_PAD src0_sel:WORD_1
	v_cvt_f32_f16_e32 v24, v22
	v_cvt_f32_f16_sdwa v25, v22 dst_sel:DWORD dst_unused:UNUSED_PAD src0_sel:WORD_1
	v_cvt_f32_f16_e32 v32, v23
	v_cvt_f32_f16_sdwa v33, v23 dst_sel:DWORD dst_unused:UNUSED_PAD src0_sel:WORD_1
	v_exp_f32_e32 v4, v4
	v_exp_f32_e32 v5, v5
	v_exp_f32_e32 v6, v6
	v_exp_f32_e32 v7, v7
	v_pk_add_f32 v[30:31], v[24:25], -1.0 op_sel_hi:[1,0]
	v_lshlrev_b32_e32 v12, 16, v20
	v_and_b32_e32 v13, 0xffff0000, v20
	v_pk_fma_f32 v[30:31], v[0:1], v[30:31], 1.0 op_sel_hi:[1,1,0]
	v_pk_add_f32 v[36:37], v[32:33], -1.0 op_sel_hi:[1,0]
	v_pk_mul_f32 v[30:31], v[30:31], v[12:13]
	v_lshlrev_b32_e32 v12, 16, v21
	v_and_b32_e32 v13, 0xffff0000, v21
	v_pk_fma_f32 v[36:37], v[2:3], v[36:37], 1.0 op_sel_hi:[1,1,0]
	v_cvt_pk_f16_f32 v10, v9, v18
	v_mul_f32_e32 v29, v24, v9
	v_mul_f32_e32 v25, v25, v18
	v_mul_f32_e32 v35, v32, v28
	v_pk_mul_f32 v[36:37], v[36:37], v[12:13]
	v_mul_f32_e32 v9, v33, v34
	v_cvt_pk_f16_f32 v20, v29, v25
	v_cvt_pk_f16_f32 v22, v30, v31
	v_cvt_pk_f16_f32 v21, v35, v9
	v_cvt_pk_f16_f32 v23, v36, v37
	ds_write_b128 v70, v[4:7] offset:49152
	ds_write_b32 v70, v29 offset:49664
	ds_write_b32 v70, v25 offset:49668
	ds_write_b32 v70, v35 offset:49672
	ds_write_b32 v70, v9 offset:49676
	ds_write_b64 v70, v[30:31] offset:49920
	ds_write_b64 v70, v[36:37] offset:49928
	v_mul_f32_e32 v4, v4, v27
	v_mul_f32_e32 v5, v5, v26
	v_cvt_pk_f16_f32 v11, v28, v34
	v_and_b32_e32 v18, 0xffff0000, v19
	v_lshlrev_b32_e32 v19, 16, v19
	v_cvt_pk_f16_f32 v12, v27, v26
	v_fma_f32 v4, v30, v27, 0
	v_mov_b32_e32 v28, v31
	v_mov_b32_e32 v5, v180
	v_pk_mov_b32 v[20:21], v[18:19], v[26:27] op_sel:[1,0]
	v_pk_fma_f32 v[4:5], v[28:29], v[26:27], v[4:5]
	v_mov_b32_e32 v24, v36
	v_mul_f32_e32 v6, v6, v19
	v_mul_f32_e32 v7, v7, v18
	v_pk_fma_f32 v[4:5], v[24:25], v[20:21], v[4:5]
	v_mov_b32_e32 v34, v37
	v_cvt_pk_f16_f32 v13, v19, v18
	v_pk_fma_f32 v[4:5], v[34:35], v[18:19], v[4:5]
	v_mov_b32_e32 v6, v180
	v_mul_f32_e32 v7, v9, v18
	s_waitcnt vmcnt(0)
	v_lshlrev_b32_e32 v8, 16, v94
	v_mov_b32_dpp v6, v4 row_ror:1 row_mask:0xf bank_mask:0xf
	v_pk_add_f32 v[4:5], v[4:5], v[6:7]
	v_mov_b32_e32 v7, v180
	v_mov_b32_e32 v6, v180
	ds_write_b128 v70, v[10:13] offset:49408
	v_mov_b32_dpp v7, v5 row_ror:1 row_mask:0xf bank_mask:0xf
	v_mov_b32_dpp v6, v4 row_ror:2 row_mask:0xf bank_mask:0xf
	v_pk_add_f32 v[4:5], v[4:5], v[6:7]
	v_mov_b32_e32 v7, v180
	v_mov_b32_e32 v6, v180
	s_nop 0
	v_mov_b32_dpp v7, v5 row_ror:2 row_mask:0xf bank_mask:0xf
	v_mov_b32_dpp v6, v4 row_ror:4 row_mask:0xf bank_mask:0xf
	v_pk_add_f32 v[4:5], v[4:5], v[6:7]
	v_mov_b32_e32 v7, v180
	v_mov_b32_e32 v6, v180
	s_nop 0
	v_mov_b32_dpp v7, v5 row_ror:4 row_mask:0xf bank_mask:0xf
	v_mov_b32_dpp v6, v4 row_ror:8 row_mask:0xf bank_mask:0xf
	v_pk_add_f32 v[4:5], v[4:5], v[6:7]
	v_mov_b32_e32 v7, v180
	v_pk_mul_f32 v[10:11], v[4:5], v[8:9]
	s_nop 0
	v_mov_b32_dpp v7, v5 row_ror:8 row_mask:0xf bank_mask:0xf
	v_pk_add_f32 v[4:5], v[4:5], v[6:7]
	s_nop 0
	v_mov_b32_e32 v11, v5
	v_pk_mul_f32 v[4:5], v[10:11], s[10:11] op_sel_hi:[1,0]
	v_mov_b32_e32 v11, v180
	v_mov_b32_e32 v9, v4
	v_cndmask_b32_e64 v4, v71, v62, s[42:43]
	v_mov_b32_e32 v10, v5
	v_ashrrev_i32_e32 v5, 31, v4
	v_lshl_add_u64 v[4:5], v[4:5], 0, s[80:81]
	v_lshlrev_b64 v[18:19], 9, v[4:5]
	v_or_b32_e32 v18, s37, v18
	v_or_b32_e32 v4, v18, v14
	v_mov_b32_e32 v5, v19
	v_lshlrev_b64 v[12:13], 1, v[4:5]
	ds_write_b32 v59, v8 offset:3072
	v_lshl_add_u64 v[4:5], s[44:45], 0, v[12:13]
	v_lshl_add_u64 v[6:7], s[46:47], 0, v[12:13]
	v_lshl_add_u64 v[8:9], s[8:9], 0, v[12:13]
	v_lshl_add_u64 v[10:11], s[34:35], 0, v[12:13]
	v_lshl_add_u64 v[12:13], s[28:29], 0, v[12:13]
	v_lshl_add_u64 v[18:19], v[18:19], 1, v[16:17]
	global_load_dwordx2 v[12:13], v[12:13], off
	s_nop 0
	global_load_ushort v48, v[18:19], off
	v_cndmask_b32_e64 v18, v73, v72, s[42:43]
	v_ashrrev_i32_e32 v19, 31, v18
	v_lshl_add_u64 v[18:19], v[18:19], 0, s[80:81]
	v_lshlrev_b64 v[28:29], 9, v[18:19]
	v_or_b32_e32 v28, s37, v28
	v_or_b32_e32 v18, v28, v14
	v_mov_b32_e32 v19, v29
	v_lshlrev_b64 v[26:27], 1, v[18:19]
	v_lshl_add_u64 v[18:19], s[44:45], 0, v[26:27]
	v_lshl_add_u64 v[20:21], s[46:47], 0, v[26:27]
	v_lshl_add_u64 v[22:23], s[8:9], 0, v[26:27]
	v_lshl_add_u64 v[24:25], s[34:35], 0, v[26:27]
	v_lshl_add_u64 v[26:27], s[28:29], 0, v[26:27]
	v_lshl_add_u64 v[28:29], v[28:29], 1, v[16:17]
	global_load_dwordx2 v[26:27], v[26:27], off
	s_nop 0
	global_load_ushort v49, v[28:29], off
	v_cndmask_b32_e64 v28, v75, v74, s[42:43]
	v_ashrrev_i32_e32 v29, 31, v28
	v_lshl_add_u64 v[28:29], v[28:29], 0, s[80:81]
	v_lshlrev_b64 v[38:39], 9, v[28:29]
	v_or_b32_e32 v38, s37, v38
	v_or_b32_e32 v28, v38, v14
	v_mov_b32_e32 v29, v39
	v_lshlrev_b64 v[36:37], 1, v[28:29]
	v_lshl_add_u64 v[28:29], s[44:45], 0, v[36:37]
	v_lshl_add_u64 v[30:31], s[46:47], 0, v[36:37]
	v_lshl_add_u64 v[32:33], s[8:9], 0, v[36:37]
	v_lshl_add_u64 v[34:35], s[34:35], 0, v[36:37]
	v_lshl_add_u64 v[36:37], s[28:29], 0, v[36:37]
	v_lshl_add_u64 v[38:39], v[38:39], 1, v[16:17]
	global_load_dwordx2 v[36:37], v[36:37], off
	s_nop 0
	global_load_ushort v50, v[38:39], off
	v_cndmask_b32_e64 v38, v77, v76, s[42:43]
	v_ashrrev_i32_e32 v39, 31, v38
	v_lshl_add_u64 v[38:39], v[38:39], 0, s[80:81]
	v_lshlrev_b64 v[52:53], 9, v[38:39]
	v_or_b32_e32 v52, s37, v52
	v_or_b32_e32 v38, v52, v14
	v_mov_b32_e32 v39, v53
	v_lshlrev_b64 v[46:47], 1, v[38:39]
	v_lshl_add_u64 v[38:39], s[44:45], 0, v[46:47]
	v_lshl_add_u64 v[40:41], s[46:47], 0, v[46:47]
	v_lshl_add_u64 v[42:43], s[8:9], 0, v[46:47]
	v_lshl_add_u64 v[44:45], s[34:35], 0, v[46:47]
	v_lshl_add_u64 v[46:47], s[28:29], 0, v[46:47]
	v_lshl_add_u64 v[52:53], v[52:53], 1, v[16:17]
	global_load_dwordx2 v[4:5], v[4:5], off
	s_nop 0
	global_load_dwordx2 v[6:7], v[6:7], off
	s_nop 0
	global_load_dwordx2 v[8:9], v[8:9], off
	s_nop 0
	global_load_dwordx2 v[10:11], v[10:11], off
	s_nop 0
	global_load_dwordx2 v[18:19], v[18:19], off
	s_nop 0
	global_load_dwordx2 v[20:21], v[20:21], off
	s_nop 0
	global_load_dwordx2 v[22:23], v[22:23], off
	s_nop 0
	global_load_dwordx2 v[24:25], v[24:25], off
	s_nop 0
	global_load_dwordx2 v[28:29], v[28:29], off
	s_nop 0
	global_load_dwordx2 v[30:31], v[30:31], off
	s_nop 0
	global_load_dwordx2 v[32:33], v[32:33], off
	s_nop 0
	global_load_dwordx2 v[34:35], v[34:35], off
	s_nop 0
	global_load_dwordx2 v[38:39], v[38:39], off
	s_nop 0
	global_load_dwordx2 v[40:41], v[40:41], off
	s_nop 0
	global_load_dwordx2 v[42:43], v[42:43], off
	s_nop 0
	global_load_dwordx2 v[44:45], v[44:45], off
	s_nop 0
	global_load_dwordx2 v[46:47], v[46:47], off
	s_nop 0
	global_load_ushort v51, v[52:53], off
	s_waitcnt lgkmcnt(0)
	s_barrier
	v_mov_b32_e32 v52, v80
	v_add_u32_e32 v106, 0x80, v61
	v_sub_u32_e32 v107, 0x1f7f, v61
	v_cndmask_b32_e64 v106, v107, v106, s[42:43]
	v_add_u32_e32 v106, s80, v106
	v_lshlrev_b32_e32 v106, 9, v106
	v_or_b32_e32 v106, s37, v106
	v_or_b32_e32 v110, v106, v14
	v_lshlrev_b32_e32 v110, 1, v110
	v_lshlrev_b32_e32 v106, 1, v106
	s_lshl_b32 s13, s64, 5
	v_lshl_or_b32 v107, v15, 1, s13
	v_add_u32_e32 v106, v106, v107
	s_and_b64 s[16:17], s[42:43], exec
	s_mov_b32 s12, 0x10000
	s_cselect_b32 s12, s12, 0xffff0000
	s_movk_i32 s13, 0x4000
	s_cselect_b32 s13, s13, 0xffffc000
	v_add_u32_e32 v111, s13, v110
	v_add_u32_e32 v112, s13, v111
	v_add_u32_e32 v113, s13, v112
	v_add_u32_e32 v107, s13, v106
	v_add_u32_e32 v108, s13, v107
	v_add_u32_e32 v109, s13, v108
	s_add_u32 s14, s30, 0x17af0000
	s_addc_u32 s15, s31, 0
	s_branch .LBB0_61

.LBB0_61:
	s_cmpk_eq_i32 s4, 0xe040
	s_cbranch_scc1 .LBB0_63
	s_waitcnt vmcnt(0)
	v_cvt_f32_f16_e64 v54, -v12
	v_cvt_f32_f16_sdwa v55, -v12 dst_sel:DWORD dst_unused:UNUSED_PAD src0_sel:WORD_1
	v_cvt_f32_f16_e64 v56, -v13
	v_cvt_f32_f16_sdwa v57, -v13 dst_sel:DWORD dst_unused:UNUSED_PAD src0_sel:WORD_1
	s_waitcnt vmcnt(14)
	v_cvt_f32_f16_e32 v86, v10
	v_cvt_f32_f16_sdwa v87, v10 dst_sel:DWORD dst_unused:UNUSED_PAD src0_sel:WORD_1
	v_cvt_f32_f16_e32 v98, v11
	v_cvt_f32_f16_sdwa v99, v11 dst_sel:DWORD dst_unused:UNUSED_PAD src0_sel:WORD_1
	v_exp_f32_e32 v54, v54
	v_exp_f32_e32 v55, v55
	v_exp_f32_e32 v56, v56
	v_exp_f32_e32 v57, v57
	v_pk_add_f32 v[94:95], v[86:87], -1.0 op_sel_hi:[1,0]
	v_pk_add_f32 v[104:105], v[98:99], -1.0 op_sel_hi:[1,0]
	s_and_b32 s7, s5, 0x10000
	s_lshr_b32 s100, s7, 4
	v_add_u32_e32 v60, s100, v59
	v_lshlrev_b32_e32 v53, 16, v8
	v_and_b32_e32 v81, 0xffff0000, v8
	v_lshlrev_b32_e32 v83, 16, v9
	v_and_b32_e32 v92, 0xffff0000, v9
	v_lshlrev_b32_e32 v88, 16, v6
	v_and_b32_e32 v89, 0xffff0000, v6
	v_pk_fma_f32 v[94:95], v[0:1], v[94:95], 1.0 op_sel_hi:[1,1,0]
	v_lshlrev_b32_e32 v100, 16, v7
	v_and_b32_e32 v101, 0xffff0000, v7
	v_pk_fma_f32 v[104:105], v[2:3], v[104:105], 1.0 op_sel_hi:[1,1,0]
	v_lshlrev_b32_e32 v91, 16, v4
	v_and_b32_e32 v90, 0xffff0000, v4
	v_cvt_pk_f16_f32 v84, v53, v81
	v_mul_f32_e32 v114, v86, v53
	v_pk_mul_f32 v[118:119], v[94:95], v[88:89]
	v_mul_f32_e32 v115, v87, v81
	v_mul_f32_e32 v116, v98, v83
	v_pk_mul_f32 v[120:121], v[104:105], v[100:101]
	v_mul_f32_e32 v117, v99, v92
	v_add_u32_e32 v53, s7, v70
	ds_write_b128 v53, v[54:57]
	ds_write_b128 v53, v[114:117] offset:512
	ds_write_b128 v53, v[118:121] offset:768
	v_cvt_pk_f16_f32 v85, v83, v92
	v_and_b32_e32 v88, 0xffff0000, v5
	v_lshlrev_b32_e32 v89, 16, v5
	v_cvt_pk_f16_f32 v86, v91, v90
	v_cvt_pk_f16_f32 v87, v89, v88
	v_lshlrev_b32_e32 v82, 16, v48
	ds_write_b128 v53, v[84:87] offset:256
	s_waitcnt vmcnt(10)
	v_cvt_f32_f16_e32 v86, v24
	v_cvt_f32_f16_sdwa v87, v24 dst_sel:DWORD dst_unused:UNUSED_PAD src0_sel:WORD_1
	v_cvt_f32_f16_e32 v98, v25
	v_cvt_f32_f16_e64 v56, -v27
	v_cvt_f32_f16_sdwa v57, -v27 dst_sel:DWORD dst_unused:UNUSED_PAD src0_sel:WORD_1
	v_cvt_f32_f16_e64 v54, -v26
	v_cvt_f32_f16_sdwa v55, -v26 dst_sel:DWORD dst_unused:UNUSED_PAD src0_sel:WORD_1
	v_cvt_f32_f16_sdwa v99, v25 dst_sel:DWORD dst_unused:UNUSED_PAD src0_sel:WORD_1
	v_exp_f32_e32 v56, v56
	v_exp_f32_e32 v54, v54
	v_exp_f32_e32 v55, v55
	v_exp_f32_e32 v57, v57
	v_pk_add_f32 v[94:95], v[86:87], -1.0 op_sel_hi:[1,0]
	v_pk_add_f32 v[104:105], v[98:99], -1.0 op_sel_hi:[1,0]
	ds_write_b32 v60, v82 offset:0
	v_lshlrev_b32_e32 v81, 16, v22
	v_and_b32_e32 v83, 0xffff0000, v22
	v_lshlrev_b32_e32 v92, 16, v23
	v_and_b32_e32 v96, 0xffff0000, v23
	v_lshlrev_b32_e32 v88, 16, v20
	v_and_b32_e32 v89, 0xffff0000, v20
	v_pk_fma_f32 v[94:95], v[0:1], v[94:95], 1.0 op_sel_hi:[1,1,0]
	v_lshlrev_b32_e32 v100, 16, v21
	v_and_b32_e32 v101, 0xffff0000, v21
	v_pk_fma_f32 v[104:105], v[2:3], v[104:105], 1.0 op_sel_hi:[1,1,0]
	v_lshlrev_b32_e32 v91, 16, v18
	v_and_b32_e32 v90, 0xffff0000, v18
	v_cvt_pk_f16_f32 v84, v81, v83
	v_mul_f32_e32 v114, v86, v81
	v_pk_mul_f32 v[118:119], v[94:95], v[88:89]
	v_mul_f32_e32 v115, v87, v83
	v_mul_f32_e32 v116, v98, v92
	v_pk_mul_f32 v[120:121], v[104:105], v[100:101]
	v_mul_f32_e32 v117, v99, v96
	ds_write_b128 v53, v[54:57] offset:16384
	ds_write_b128 v53, v[114:117] offset:16896
	ds_write_b128 v53, v[118:121] offset:17152
	v_cvt_pk_f16_f32 v85, v92, v96
	v_and_b32_e32 v88, 0xffff0000, v19
	v_lshlrev_b32_e32 v89, 16, v19
	v_cvt_pk_f16_f32 v86, v91, v90
	v_cvt_pk_f16_f32 v87, v89, v88
	v_lshlrev_b32_e32 v82, 16, v49
	ds_write_b128 v53, v[84:87] offset:16640
	s_waitcnt vmcnt(6)
	v_cvt_f32_f16_e32 v86, v34
	v_cvt_f32_f16_sdwa v87, v34 dst_sel:DWORD dst_unused:UNUSED_PAD src0_sel:WORD_1
	v_cvt_f32_f16_e32 v98, v35
	v_cvt_f32_f16_e64 v56, -v37
	v_cvt_f32_f16_sdwa v57, -v37 dst_sel:DWORD dst_unused:UNUSED_PAD src0_sel:WORD_1
	v_cvt_f32_f16_e64 v54, -v36
	v_cvt_f32_f16_sdwa v55, -v36 dst_sel:DWORD dst_unused:UNUSED_PAD src0_sel:WORD_1
	v_cvt_f32_f16_sdwa v99, v35 dst_sel:DWORD dst_unused:UNUSED_PAD src0_sel:WORD_1
	v_exp_f32_e32 v56, v56
	v_exp_f32_e32 v54, v54
	v_exp_f32_e32 v55, v55
	v_exp_f32_e32 v57, v57
	v_pk_add_f32 v[94:95], v[86:87], -1.0 op_sel_hi:[1,0]
	v_pk_add_f32 v[104:105], v[98:99], -1.0 op_sel_hi:[1,0]
	ds_write_b32 v60, v82 offset:1024
	v_lshlrev_b32_e32 v81, 16, v32
	v_and_b32_e32 v83, 0xffff0000, v32
	v_lshlrev_b32_e32 v92, 16, v33
	v_and_b32_e32 v96, 0xffff0000, v33
	v_lshlrev_b32_e32 v88, 16, v30
	v_and_b32_e32 v89, 0xffff0000, v30
	v_pk_fma_f32 v[94:95], v[0:1], v[94:95], 1.0 op_sel_hi:[1,1,0]
	v_lshlrev_b32_e32 v100, 16, v31
	v_and_b32_e32 v101, 0xffff0000, v31
	v_pk_fma_f32 v[104:105], v[2:3], v[104:105], 1.0 op_sel_hi:[1,1,0]
	v_lshlrev_b32_e32 v91, 16, v28
	v_and_b32_e32 v90, 0xffff0000, v28
	v_cvt_pk_f16_f32 v84, v81, v83
	v_mul_f32_e32 v114, v86, v81
	v_pk_mul_f32 v[118:119], v[94:95], v[88:89]
	v_mul_f32_e32 v115, v87, v83
	v_mul_f32_e32 v116, v98, v92
	v_pk_mul_f32 v[120:121], v[104:105], v[100:101]
	v_mul_f32_e32 v117, v99, v96
	ds_write_b128 v53, v[54:57] offset:32768
	ds_write_b128 v53, v[114:117] offset:33280
	ds_write_b128 v53, v[118:121] offset:33536
	v_cvt_pk_f16_f32 v85, v92, v96
	v_and_b32_e32 v88, 0xffff0000, v29
	v_lshlrev_b32_e32 v89, 16, v29
	v_cvt_pk_f16_f32 v86, v91, v90
	v_cvt_pk_f16_f32 v87, v89, v88
	v_lshlrev_b32_e32 v82, 16, v50
	ds_write_b128 v53, v[84:87] offset:33024
	s_waitcnt vmcnt(2)
	v_cvt_f32_f16_e32 v86, v44
	v_cvt_f32_f16_sdwa v87, v44 dst_sel:DWORD dst_unused:UNUSED_PAD src0_sel:WORD_1
	v_cvt_f32_f16_e32 v98, v45
	s_waitcnt vmcnt(1)
	v_cvt_f32_f16_e64 v56, -v47
	v_cvt_f32_f16_sdwa v57, -v47 dst_sel:DWORD dst_unused:UNUSED_PAD src0_sel:WORD_1
	v_cvt_f32_f16_e64 v54, -v46
	v_cvt_f32_f16_sdwa v55, -v46 dst_sel:DWORD dst_unused:UNUSED_PAD src0_sel:WORD_1
	v_cvt_f32_f16_sdwa v99, v45 dst_sel:DWORD dst_unused:UNUSED_PAD src0_sel:WORD_1
	v_exp_f32_e32 v56, v56
	v_exp_f32_e32 v54, v54
	v_exp_f32_e32 v55, v55
	v_exp_f32_e32 v57, v57
	v_pk_add_f32 v[94:95], v[86:87], -1.0 op_sel_hi:[1,0]
	v_pk_add_f32 v[104:105], v[98:99], -1.0 op_sel_hi:[1,0]
	ds_write_b32 v60, v82 offset:2048
	v_lshlrev_b32_e32 v81, 16, v42
	v_and_b32_e32 v83, 0xffff0000, v42
	v_lshlrev_b32_e32 v92, 16, v43
	v_and_b32_e32 v96, 0xffff0000, v43
	v_lshlrev_b32_e32 v88, 16, v40
	v_and_b32_e32 v89, 0xffff0000, v40
	v_pk_fma_f32 v[94:95], v[0:1], v[94:95], 1.0 op_sel_hi:[1,1,0]
	v_lshlrev_b32_e32 v100, 16, v41
	v_and_b32_e32 v101, 0xffff0000, v41
	v_pk_fma_f32 v[104:105], v[2:3], v[104:105], 1.0 op_sel_hi:[1,1,0]
	v_lshlrev_b32_e32 v91, 16, v38
	v_and_b32_e32 v90, 0xffff0000, v38
	v_cvt_pk_f16_f32 v84, v81, v83
	v_mul_f32_e32 v114, v86, v81
	v_pk_mul_f32 v[118:119], v[94:95], v[88:89]
	v_mul_f32_e32 v115, v87, v83
	v_mul_f32_e32 v116, v98, v92
	v_pk_mul_f32 v[120:121], v[104:105], v[100:101]
	v_mul_f32_e32 v117, v99, v96
	ds_write_b128 v53, v[54:57] offset:49152
	ds_write_b128 v53, v[114:117] offset:49664
	ds_write_b128 v53, v[118:121] offset:49920
	v_cvt_pk_f16_f32 v85, v92, v96
	v_and_b32_e32 v88, 0xffff0000, v39
	v_lshlrev_b32_e32 v89, 16, v39
	v_cvt_pk_f16_f32 v86, v91, v90
	v_cvt_pk_f16_f32 v87, v89, v88
	s_waitcnt vmcnt(0)
	v_lshlrev_b32_e32 v82, 16, v51
	ds_write_b128 v53, v[84:87] offset:49408
	s_nop 0
	s_nop 0
	s_nop 0
	s_nop 0
	ds_write_b32 v60, v82 offset:3072
.LBB0_63:
	s_cmpk_gt_u32 s6, 0x7d
	s_cbranch_scc1 .LBB0_60
	s_waitcnt vmcnt(0)
	global_load_dwordx2 v[4:5], v110, s[44:45]
	global_load_dwordx2 v[6:7], v110, s[46:47]
	global_load_dwordx2 v[8:9], v110, s[8:9]
	global_load_dwordx2 v[10:11], v110, s[34:35]
	global_load_dwordx2 v[12:13], v110, s[28:29]
	global_load_ushort v48, v106, s[14:15]
	global_load_dwordx2 v[18:19], v111, s[44:45]
	global_load_dwordx2 v[20:21], v111, s[46:47]
	global_load_dwordx2 v[22:23], v111, s[8:9]
	global_load_dwordx2 v[24:25], v111, s[34:35]
	global_load_dwordx2 v[26:27], v111, s[28:29]
	global_load_ushort v49, v107, s[14:15]
	global_load_dwordx2 v[28:29], v112, s[44:45]
	global_load_dwordx2 v[30:31], v112, s[46:47]
	global_load_dwordx2 v[32:33], v112, s[8:9]
	global_load_dwordx2 v[34:35], v112, s[34:35]
	global_load_dwordx2 v[36:37], v112, s[28:29]
	global_load_ushort v50, v108, s[14:15]
	global_load_dwordx2 v[38:39], v113, s[44:45]
	global_load_dwordx2 v[40:41], v113, s[46:47]
	global_load_dwordx2 v[42:43], v113, s[8:9]
	global_load_dwordx2 v[44:45], v113, s[34:35]
	global_load_dwordx2 v[46:47], v113, s[28:29]
	global_load_ushort v51, v109, s[14:15]
	v_add_u32_e32 v110, s12, v110
	v_add_u32_e32 v106, s12, v106
	v_add_u32_e32 v111, s12, v111
	v_add_u32_e32 v107, s12, v107
	v_add_u32_e32 v112, s12, v112
	v_add_u32_e32 v108, s12, v108
	v_add_u32_e32 v113, s12, v113
	v_add_u32_e32 v109, s12, v109
	s_branch .LBB0_60
